# attention loops: LDS write pass of the next K/V tile moved behind the first MFMAs of the iteration (nothing pending before the barrier), loads re-issued right after; same numerics
# speedup vs baseline: 1.0628x; 1.0024x over previous
.LBB0_538:
	v_add_f32_e32 v233, v233, v249
	v_add_f32_e32 v245, v245, v248
	v_lshl_add_u64 v[206:207], v[206:207], 0, s[28:29]
	s_cmpk_lg_i32 s17, 0x100
	v_lshl_add_u64 v[208:209], v[208:209], 0, s[26:27]
	s_waitcnt lgkmcnt(0)
	s_barrier
	s_cbranch_scc0 .LBB0_540
	s_mov_b32 s14, s17
	s_cmpk_lg_i32 s14, 0xfe
	s_cselect_b64 s[38:39], -1, 0
	s_cmpk_eq_i32 s14, 0xfe
	s_branch .Lgq_loop
.Lgq_loop:
	global_load_dwordx4 v[160:163], v[206:207], off
	global_load_dwordx4 v[164:167], v[208:209], off
.Lgq_body:
	s_and_b32 s12, s14, 2
	s_mulk_i32 s12, 0x2400
	s_add_i32 s17, s12, 0
	v_add3_u32 v248, s17, v200, v244
	v_add3_u32 v249, s17, v242, v200
	ds_read_b128 v[210:213], v248
	ds_read_b128 v[214:217], v248 offset:32
	ds_read_b128 v[218:221], v248 offset:64
	ds_read_b128 v[222:225], v248 offset:96
	s_waitcnt lgkmcnt(3)
	v_mfma_f32_32x32x16_bf16 v[144:159], v[210:213], v[168:171], v[80:95]
	s_waitcnt lgkmcnt(2)
	v_mfma_f32_32x32x16_bf16 v[144:159], v[214:217], v[172:175], v[144:159]
	s_waitcnt lgkmcnt(1)
	v_mfma_f32_32x32x16_bf16 v[144:159], v[218:221], v[176:179], v[144:159]
	s_waitcnt lgkmcnt(0)
	v_mfma_f32_32x32x16_bf16 v[144:159], v[222:225], v[180:183], v[144:159]
	s_cmpk_eq_i32 s14, 0xfe
	s_cbranch_scc1 .Lgq_nostage
	s_add_i32 s12, s14, 2
	s_and_b32 s12, s12, 2
	s_mulk_i32 s12, 0x2400
	v_add_u32_e32 v250, s12, v243
	s_waitcnt vmcnt(1)
	ds_write_b128 v250, v[160:163]
	s_waitcnt vmcnt(0)
	ds_write_b128 v250, v[164:167] offset:9216
	v_lshl_add_u64 v[206:207], v[206:207], 0, s[28:29]
	v_lshl_add_u64 v[208:209], v[208:209], 0, s[26:27]
	s_cmpk_eq_i32 s14, 0xfc
	s_cbranch_scc1 .Lgq_nostage
	global_load_dwordx4 v[160:163], v[206:207], off
	global_load_dwordx4 v[164:167], v[208:209], off
.Lgq_nostage:
	s_nop 9
	v_mfma_f32_32x32x16_bf16 v[112:127], v[210:213], v[184:187], v[64:79]
	ds_read_b128 v[210:213], v248 offset:4608
	v_exp_f32_e32 v144, v144
	v_exp_f32_e32 v145, v145
	v_exp_f32_e32 v146, v146
	v_exp_f32_e32 v147, v147
	v_add_f32_e32 v226, v144, v146
	v_mfma_f32_32x32x16_bf16 v[112:127], v[214:217], v[188:191], v[112:127]
	ds_read_b128 v[214:217], v248 offset:4640
	v_add_f32_e32 v227, v145, v147
	v_exp_f32_e32 v148, v148
	v_exp_f32_e32 v149, v149
	v_add_f32_e32 v226, v226, v148
	v_add_f32_e32 v227, v227, v149
	v_exp_f32_e32 v150, v150
	v_mfma_f32_32x32x16_bf16 v[112:127], v[218:221], v[192:195], v[112:127]
	ds_read_b128 v[218:221], v248 offset:4672
	v_exp_f32_e32 v151, v151
	v_add_f32_e32 v226, v226, v150
	v_add_f32_e32 v227, v227, v151
	v_exp_f32_e32 v152, v152
	v_exp_f32_e32 v153, v153
	v_add_f32_e32 v226, v226, v152
	v_mfma_f32_32x32x16_bf16 v[112:127], v[222:225], v[196:199], v[112:127]
	ds_read_b128 v[222:225], v248 offset:4704
	v_add_f32_e32 v227, v227, v153
	v_exp_f32_e32 v154, v154
	v_exp_f32_e32 v155, v155
	v_add_f32_e32 v226, v226, v154
	v_add_f32_e32 v227, v227, v155
	v_exp_f32_e32 v156, v156
	s_waitcnt lgkmcnt(3)
	v_mfma_f32_32x32x16_bf16 v[128:143], v[210:213], v[168:171], v[80:95]
	v_exp_f32_e32 v157, v157
	v_add_f32_e32 v226, v226, v156
	v_add_f32_e32 v227, v227, v157
	v_exp_f32_e32 v158, v158
	v_exp_f32_e32 v159, v159
	v_add_f32_e32 v226, v226, v158
	s_waitcnt lgkmcnt(2)
	v_mfma_f32_32x32x16_bf16 v[128:143], v[214:217], v[172:175], v[128:143]
	v_add_f32_e32 v227, v227, v159
	v_exp_f32_e32 v112, v112
	v_exp_f32_e32 v113, v113
	v_exp_f32_e32 v114, v114
	v_exp_f32_e32 v115, v115
	s_waitcnt lgkmcnt(1)
	v_mfma_f32_32x32x16_bf16 v[128:143], v[218:221], v[176:179], v[128:143]
	v_add_f32_e32 v228, v112, v114
	v_add_f32_e32 v229, v113, v115
	v_exp_f32_e32 v116, v116
	v_exp_f32_e32 v117, v117
	v_add_f32_e32 v228, v228, v116
	v_add_f32_e32 v229, v229, v117
	v_exp_f32_e32 v118, v118
	s_waitcnt lgkmcnt(0)
	v_mfma_f32_32x32x16_bf16 v[128:143], v[222:225], v[180:183], v[128:143]
	v_exp_f32_e32 v119, v119
	v_add_f32_e32 v228, v228, v118
	v_add_f32_e32 v229, v229, v119
	v_cvt_pk_bf16_f32 v144, v144, v145
	v_cvt_pk_bf16_f32 v145, v146, v147
	v_cvt_pk_bf16_f32 v146, v148, v149
	v_cvt_pk_bf16_f32 v147, v150, v151
	v_cvt_pk_bf16_f32 v112, v112, v113
	v_mfma_f32_32x32x16_bf16 v[96:111], v[210:213], v[184:187], v[64:79]
	ds_read_b128 v[210:213], v249 offset:9216
	v_cvt_pk_bf16_f32 v113, v114, v115
	v_cvt_pk_bf16_f32 v114, v116, v117
	v_cvt_pk_bf16_f32 v115, v118, v119
	v_exp_f32_e32 v120, v120
	v_exp_f32_e32 v121, v121
	v_add_f32_e32 v228, v228, v120
	v_add_f32_e32 v229, v229, v121
	v_mfma_f32_32x32x16_bf16 v[96:111], v[214:217], v[188:191], v[96:111]
	ds_read_b128 v[214:217], v249 offset:13824
	v_exp_f32_e32 v122, v122
	v_exp_f32_e32 v123, v123
	v_add_f32_e32 v228, v228, v122
	v_add_f32_e32 v229, v229, v123
	v_exp_f32_e32 v124, v124
	v_exp_f32_e32 v125, v125
	v_mfma_f32_32x32x16_bf16 v[96:111], v[218:221], v[192:195], v[96:111]
	ds_read_b128 v[218:221], v249 offset:9248
	v_add_f32_e32 v228, v228, v124
	v_add_f32_e32 v229, v229, v125
	v_exp_f32_e32 v126, v126
	v_exp_f32_e32 v127, v127
	v_add_f32_e32 v228, v228, v126
	v_add_f32_e32 v229, v229, v127
	v_cvt_pk_bf16_f32 v152, v152, v153
	v_mfma_f32_32x32x16_bf16 v[96:111], v[222:225], v[196:199], v[96:111]
	ds_read_b128 v[222:225], v249 offset:13856
	v_cvt_pk_bf16_f32 v153, v154, v155
	v_cvt_pk_bf16_f32 v154, v156, v157
	v_cvt_pk_bf16_f32 v155, v158, v159
	v_cvt_pk_bf16_f32 v120, v120, v121
	v_cvt_pk_bf16_f32 v121, v122, v123
	v_cvt_pk_bf16_f32 v122, v124, v125
	v_cvt_pk_bf16_f32 v123, v126, v127
	v_exp_f32_e32 v128, v128
	s_waitcnt lgkmcnt(3)
	s_nop 1
	v_mfma_f32_32x32x16_bf16 v[48:63], v[210:213], v[144:147], v[48:63]
	v_exp_f32_e32 v129, v129
	v_add_f32_e32 v226, v226, v128
	v_add_f32_e32 v227, v227, v129
	v_exp_f32_e32 v130, v130
	v_exp_f32_e32 v131, v131
	v_add_f32_e32 v226, v226, v130
	v_mfma_f32_32x32x16_bf16 v[16:31], v[210:213], v[112:115], v[16:31]
	ds_read_b128 v[210:213], v249 offset:9280
	v_add_f32_e32 v227, v227, v131
	v_exp_f32_e32 v132, v132
	v_exp_f32_e32 v133, v133
	v_add_f32_e32 v226, v226, v132
	v_add_f32_e32 v227, v227, v133
	v_exp_f32_e32 v134, v134
	s_waitcnt lgkmcnt(3)
	v_mfma_f32_32x32x16_bf16 v[32:47], v[214:217], v[144:147], v[32:47]
	v_exp_f32_e32 v135, v135
	v_add_f32_e32 v226, v226, v134
	v_add_f32_e32 v227, v227, v135
	v_exp_f32_e32 v136, v136
	v_exp_f32_e32 v137, v137
	v_add_f32_e32 v226, v226, v136
	v_mfma_f32_32x32x16_bf16 v[0:15], v[214:217], v[112:115], v[0:15]
	ds_read_b128 v[214:217], v249 offset:13888
	v_add_f32_e32 v227, v227, v137
	v_exp_f32_e32 v138, v138
	v_exp_f32_e32 v139, v139
	v_add_f32_e32 v226, v226, v138
	v_add_f32_e32 v227, v227, v139
	v_exp_f32_e32 v140, v140
	s_waitcnt lgkmcnt(3)
	v_mfma_f32_32x32x16_bf16 v[48:63], v[218:221], v[152:155], v[48:63]
	v_exp_f32_e32 v141, v141
	v_add_f32_e32 v226, v226, v140
	v_add_f32_e32 v227, v227, v141
	v_exp_f32_e32 v142, v142
	v_exp_f32_e32 v143, v143
	v_add_f32_e32 v226, v226, v142
	v_mfma_f32_32x32x16_bf16 v[16:31], v[218:221], v[120:123], v[16:31]
	ds_read_b128 v[218:221], v249 offset:9312
	v_add_f32_e32 v227, v227, v143
	v_exp_f32_e32 v96, v96
	v_exp_f32_e32 v97, v97
	v_add_f32_e32 v228, v228, v96
	v_add_f32_e32 v229, v229, v97
	v_exp_f32_e32 v98, v98
	s_waitcnt lgkmcnt(3)
	v_mfma_f32_32x32x16_bf16 v[32:47], v[222:225], v[152:155], v[32:47]
	v_exp_f32_e32 v99, v99
	v_add_f32_e32 v228, v228, v98
	v_add_f32_e32 v229, v229, v99
	v_exp_f32_e32 v100, v100
	v_exp_f32_e32 v101, v101
	v_add_f32_e32 v228, v228, v100
	v_mfma_f32_32x32x16_bf16 v[0:15], v[222:225], v[120:123], v[0:15]
	ds_read_b128 v[222:225], v249 offset:13920
	v_add_f32_e32 v229, v229, v101
	v_exp_f32_e32 v102, v102
	v_exp_f32_e32 v103, v103
	v_add_f32_e32 v228, v228, v102
	v_add_f32_e32 v229, v229, v103
	v_cvt_pk_bf16_f32 v128, v128, v129
	v_cvt_pk_bf16_f32 v129, v130, v131
	v_cvt_pk_bf16_f32 v130, v132, v133
	v_cvt_pk_bf16_f32 v131, v134, v135
	v_cvt_pk_bf16_f32 v96, v96, v97
	v_cvt_pk_bf16_f32 v97, v98, v99
	v_cvt_pk_bf16_f32 v98, v100, v101
	v_cvt_pk_bf16_f32 v99, v102, v103
	s_waitcnt lgkmcnt(3)
	s_nop 1
	v_mfma_f32_32x32x16_bf16 v[48:63], v[210:213], v[128:131], v[48:63]
	v_exp_f32_e32 v104, v104
	v_exp_f32_e32 v105, v105
	v_add_f32_e32 v228, v228, v104
	v_add_f32_e32 v229, v229, v105
	v_exp_f32_e32 v106, v106
	v_exp_f32_e32 v107, v107
	v_mfma_f32_32x32x16_bf16 v[16:31], v[210:213], v[96:99], v[16:31]
	v_add_f32_e32 v228, v228, v106
	v_add_f32_e32 v229, v229, v107
	v_exp_f32_e32 v108, v108
	v_exp_f32_e32 v109, v109
	v_add_f32_e32 v228, v228, v108
	v_add_f32_e32 v229, v229, v109
	v_exp_f32_e32 v110, v110
	s_waitcnt lgkmcnt(2)
	v_mfma_f32_32x32x16_bf16 v[32:47], v[214:217], v[128:131], v[32:47]
	v_exp_f32_e32 v111, v111
	v_add_f32_e32 v228, v228, v110
	v_add_f32_e32 v229, v229, v111
	v_cvt_pk_bf16_f32 v136, v136, v137
	v_cvt_pk_bf16_f32 v137, v138, v139
	v_cvt_pk_bf16_f32 v138, v140, v141
	v_cvt_pk_bf16_f32 v139, v142, v143
	v_cvt_pk_bf16_f32 v104, v104, v105
	s_nop 1
	v_mfma_f32_32x32x16_bf16 v[0:15], v[214:217], v[96:99], v[0:15]
	v_cvt_pk_bf16_f32 v105, v106, v107
	v_cvt_pk_bf16_f32 v106, v108, v109
	v_cvt_pk_bf16_f32 v107, v110, v111
	v_add_f32_e32 v226, v226, v227
	v_add_f32_e32 v228, v228, v229
	v_max_f32_e32 v250, v226, v228
	s_waitcnt lgkmcnt(1)
	v_mfma_f32_32x32x16_bf16 v[48:63], v[218:221], v[136:139], v[48:63]
	v_mfma_f32_32x32x16_bf16 v[16:31], v[218:221], v[104:107], v[16:31]
	s_waitcnt lgkmcnt(0)
	v_mfma_f32_32x32x16_bf16 v[32:47], v[222:225], v[136:139], v[32:47]
	v_mfma_f32_32x32x16_bf16 v[0:15], v[222:225], v[104:107], v[0:15]
	v_cmp_lt_f32_e32 vcc, s33, v250
	s_cbranch_vccz .Lgq_norescale
	s_nop 15
	ds_bpermute_b32 v250, v230, v226
	s_waitcnt lgkmcnt(0)
	v_add_f32_e32 v250, v250, v226
	v_frexp_exp_i32_f32_e32 v250, v250
	v_max_i32_e32 v250, 1, v250
	v_add_u32_e32 v250, -1, v250
	v_cvt_f32_u32_e32 v250, v250
	v_exp_f32_e64 v251, -v250
	v_add_f32_e32 v247, v247, v250
	v_xor_b32_e32 v80, 0x80000000, v247
	v_mul_f32_e32 v245, v245, v251
	v_mul_f32_e32 v226, v226, v251
	v_mul_f32_e32 v48, v48, v251
	v_mul_f32_e32 v49, v49, v251
	v_mul_f32_e32 v50, v50, v251
	v_mul_f32_e32 v51, v51, v251
	v_mul_f32_e32 v52, v52, v251
	v_mul_f32_e32 v53, v53, v251
	v_mul_f32_e32 v54, v54, v251
	v_mul_f32_e32 v55, v55, v251
	v_mul_f32_e32 v56, v56, v251
	v_mul_f32_e32 v57, v57, v251
	v_mul_f32_e32 v58, v58, v251
	v_mul_f32_e32 v59, v59, v251
	v_mul_f32_e32 v60, v60, v251
	v_mul_f32_e32 v61, v61, v251
	v_mul_f32_e32 v62, v62, v251
	v_mul_f32_e32 v63, v63, v251
	v_mul_f32_e32 v32, v32, v251
	v_mul_f32_e32 v33, v33, v251
	v_mul_f32_e32 v34, v34, v251
	v_mul_f32_e32 v35, v35, v251
	v_mul_f32_e32 v36, v36, v251
	v_mul_f32_e32 v37, v37, v251
	v_mul_f32_e32 v38, v38, v251
	v_mul_f32_e32 v39, v39, v251
	v_mul_f32_e32 v40, v40, v251
	v_mul_f32_e32 v41, v41, v251
	v_mul_f32_e32 v42, v42, v251
	v_mul_f32_e32 v43, v43, v251
	v_mul_f32_e32 v44, v44, v251
	v_mul_f32_e32 v45, v45, v251
	v_mul_f32_e32 v46, v46, v251
	v_mul_f32_e32 v47, v47, v251
	v_mov_b32_e32 v81, v80
	v_mov_b32_e32 v82, v80
	v_mov_b32_e32 v83, v80
	v_mov_b32_e32 v84, v80
	v_mov_b32_e32 v85, v80
	v_mov_b32_e32 v86, v80
	v_mov_b32_e32 v87, v80
	v_mov_b32_e32 v88, v80
	v_mov_b32_e32 v89, v80
	v_mov_b32_e32 v90, v80
	v_mov_b32_e32 v91, v80
	v_mov_b32_e32 v92, v80
	v_mov_b32_e32 v93, v80
	v_mov_b32_e32 v94, v80
	v_mov_b32_e32 v95, v80
	ds_bpermute_b32 v250, v230, v228
	s_waitcnt lgkmcnt(0)
	v_add_f32_e32 v250, v250, v228
	v_frexp_exp_i32_f32_e32 v250, v250
	v_max_i32_e32 v250, 1, v250
	v_add_u32_e32 v250, -1, v250
	v_cvt_f32_u32_e32 v250, v250
	v_exp_f32_e64 v251, -v250
	v_add_f32_e32 v246, v246, v250
	v_xor_b32_e32 v64, 0x80000000, v246
	v_mul_f32_e32 v233, v233, v251
	v_mul_f32_e32 v228, v228, v251
	v_mul_f32_e32 v16, v16, v251
	v_mul_f32_e32 v17, v17, v251
	v_mul_f32_e32 v18, v18, v251
	v_mul_f32_e32 v19, v19, v251
	v_mul_f32_e32 v20, v20, v251
	v_mul_f32_e32 v21, v21, v251
	v_mul_f32_e32 v22, v22, v251
	v_mul_f32_e32 v23, v23, v251
	v_mul_f32_e32 v24, v24, v251
	v_mul_f32_e32 v25, v25, v251
	v_mul_f32_e32 v26, v26, v251
	v_mul_f32_e32 v27, v27, v251
	v_mul_f32_e32 v28, v28, v251
	v_mul_f32_e32 v29, v29, v251
	v_mul_f32_e32 v30, v30, v251
	v_mul_f32_e32 v31, v31, v251
	v_mul_f32_e32 v0, v0, v251
	v_mul_f32_e32 v1, v1, v251
	v_mul_f32_e32 v2, v2, v251
	v_mul_f32_e32 v3, v3, v251
	v_mul_f32_e32 v4, v4, v251
	v_mul_f32_e32 v5, v5, v251
	v_mul_f32_e32 v6, v6, v251
	v_mul_f32_e32 v7, v7, v251
	v_mul_f32_e32 v8, v8, v251
	v_mul_f32_e32 v9, v9, v251
	v_mul_f32_e32 v10, v10, v251
	v_mul_f32_e32 v11, v11, v251
	v_mul_f32_e32 v12, v12, v251
	v_mul_f32_e32 v13, v13, v251
	v_mul_f32_e32 v14, v14, v251
	v_mul_f32_e32 v15, v15, v251
	v_mov_b32_e32 v65, v64
	v_mov_b32_e32 v66, v64
	v_mov_b32_e32 v67, v64
	v_mov_b32_e32 v68, v64
	v_mov_b32_e32 v69, v64
	v_mov_b32_e32 v70, v64
	v_mov_b32_e32 v71, v64
	v_mov_b32_e32 v72, v64
	v_mov_b32_e32 v73, v64
	v_mov_b32_e32 v74, v64
	v_mov_b32_e32 v75, v64
	v_mov_b32_e32 v76, v64
	v_mov_b32_e32 v77, v64
	v_mov_b32_e32 v78, v64
	v_mov_b32_e32 v79, v64
.Lgq_norescale:
	v_add_f32_e32 v245, v245, v226
	v_add_f32_e32 v233, v233, v228
	s_add_i32 s14, s14, 2
	s_cmpk_lg_i32 s14, 0x100
	s_nop 3
	s_waitcnt lgkmcnt(0)
	s_barrier
	s_cbranch_scc1 .Lgq_body
	s_branch .LBB0_540

.Ldf_loop:
	v_lshl_add_u64 v[248:249], v[148:149], 0, v[200:201]
	v_add_co_u32_e32 v248, vcc, 0xad40000, v248
	v_lshl_add_u64 v[250:251], v[150:151], 0, v[200:201]
	s_nop 0
	v_addc_co_u32_e32 v249, vcc, 0, v249, vcc
	global_load_dwordx4 v[112:115], v[248:249], off offset:1024
	global_load_dwordx4 v[116:119], v[248:249], off offset:1152
	v_add_co_u32_e32 v248, vcc, 0x12d00000, v250
	s_nop 1
	v_addc_co_u32_e32 v249, vcc, 0, v251, vcc
	v_add_co_u32_e32 v250, vcc, 0x12e00000, v250
	s_nop 1
	v_addc_co_u32_e32 v251, vcc, 0, v251, vcc
	global_load_dwordx4 v[136:139], v[248:249], off offset:128
	global_load_dwordx4 v[140:143], v[250:251], off offset:128
.Ldf_body:
	s_bitcmp1_b32 s14, 0
	s_cselect_b32 s37, 0x9000, 0
	s_cselect_b32 s34, 0, 0x9000
	s_mul_i32 s12, s36, 0x2400
	s_add_i32 s12, s37, s12
	v_add3_u32 v246, s12, v144, v163
	v_add3_u32 v247, s37, v161, v144
	ds_read_b128 v[166:169], v246
	ds_read_b128 v[170:173], v246 offset:32
	ds_read_b128 v[174:177], v246 offset:64
	ds_read_b128 v[178:181], v246 offset:96
	ds_read_b128 v[182:185], v246 offset:4608
	ds_read_b128 v[186:189], v246 offset:4640
	ds_read_b128 v[190:193], v246 offset:4672
	ds_read_b128 v[194:197], v246 offset:4704
	s_waitcnt lgkmcnt(7)
	v_mfma_f32_32x32x16_bf16 v[96:111], v[166:169], v[120:123], v[64:79]
	s_waitcnt lgkmcnt(6)
	v_mfma_f32_32x32x16_bf16 v[96:111], v[170:173], v[124:127], v[96:111]
	s_waitcnt lgkmcnt(5)
	v_mfma_f32_32x32x16_bf16 v[96:111], v[174:177], v[128:131], v[96:111]
	s_waitcnt lgkmcnt(4)
	v_mfma_f32_32x32x16_bf16 v[96:111], v[178:181], v[132:135], v[96:111]
	ds_read_b128 v[202:205], v247 offset:18432
	ds_read_b128 v[206:209], v247 offset:23040
	ds_read_b128 v[210:213], v247 offset:27648
	ds_read_b128 v[214:217], v247 offset:32256
	s_cmpk_eq_i32 s14, 0x7f
	s_cbranch_scc1 .Ldf_nostage
	v_add_u32_e32 v156, s34, v162
	s_waitcnt vmcnt(3)
	ds_write_b128 v156, v[112:115]
	s_waitcnt vmcnt(2)
	ds_write_b128 v156, v[116:119] offset:9216
	s_waitcnt vmcnt(1)
	ds_write_b128 v156, v[136:139] offset:18432
	s_waitcnt vmcnt(0)
	ds_write_b128 v156, v[140:143] offset:27648
	v_lshl_add_u64 v[148:149], v[148:149], 0, s[28:29]
	v_lshl_add_u64 v[150:151], v[150:151], 0, s[26:27]
	s_cmpk_eq_i32 s14, 0x7e
	s_cbranch_scc1 .Ldf_nostage
	v_lshl_add_u64 v[248:249], v[148:149], 0, v[200:201]
	v_add_co_u32_e32 v248, vcc, 0xad40000, v248
	v_lshl_add_u64 v[250:251], v[150:151], 0, v[200:201]
	s_nop 0
	v_addc_co_u32_e32 v249, vcc, 0, v249, vcc
	global_load_dwordx4 v[112:115], v[248:249], off offset:1024
	global_load_dwordx4 v[116:119], v[248:249], off offset:1152
	v_add_co_u32_e32 v248, vcc, 0x12d00000, v250
	s_nop 1
	v_addc_co_u32_e32 v249, vcc, 0, v251, vcc
	v_add_co_u32_e32 v250, vcc, 0x12e00000, v250
	s_nop 1
	v_addc_co_u32_e32 v251, vcc, 0, v251, vcc
	global_load_dwordx4 v[136:139], v[248:249], off offset:128
	global_load_dwordx4 v[140:143], v[250:251], off offset:128
.Ldf_nostage:
	s_waitcnt lgkmcnt(11)
	v_mfma_f32_32x32x16_bf16 v[80:95], v[182:185], v[120:123], v[64:79]
	ds_read_b128 v[218:221], v247 offset:18464
	ds_read_b128 v[222:225], v247 offset:23072
	ds_read_b128 v[226:229], v247 offset:27680
	ds_read_b128 v[152:155], v247 offset:32288
	v_exp_f32_e32 v96, v96
	v_exp_f32_e32 v97, v97
	v_exp_f32_e32 v98, v98
	s_waitcnt lgkmcnt(14)
	v_mfma_f32_32x32x16_bf16 v[80:95], v[186:189], v[124:127], v[80:95]
	v_exp_f32_e32 v99, v99
	v_add_f32_e32 v242, v96, v98
	v_add_f32_e32 v243, v97, v99
	v_exp_f32_e32 v100, v100
	s_waitcnt lgkmcnt(13)
	v_mfma_f32_32x32x16_bf16 v[80:95], v[190:193], v[128:131], v[80:95]
	v_exp_f32_e32 v101, v101
	v_add_f32_e32 v242, v242, v100
	v_add_f32_e32 v243, v243, v101
	v_exp_f32_e32 v102, v102
	s_waitcnt lgkmcnt(12)
	v_mfma_f32_32x32x16_bf16 v[80:95], v[194:197], v[132:135], v[80:95]
	v_exp_f32_e32 v103, v103
	v_add_f32_e32 v242, v242, v102
	v_add_f32_e32 v243, v243, v103
	v_cvt_pk_bf16_f32 v96, v96, v97
	v_cvt_pk_bf16_f32 v97, v98, v99
	v_cvt_pk_bf16_f32 v98, v100, v101
	v_cvt_pk_bf16_f32 v99, v102, v103
	s_nop 1
	s_waitcnt lgkmcnt(11)
	v_mfma_f32_32x32x16_bf16 v[48:63], v[202:205], v[96:99], v[48:63]
	ds_read_b128 v[202:205], v247 offset:18496
	v_exp_f32_e32 v104, v104
	v_exp_f32_e32 v105, v105
	v_add_f32_e32 v242, v242, v104
	v_add_f32_e32 v243, v243, v105
	s_waitcnt lgkmcnt(11)
	v_mfma_f32_32x32x16_bf16 v[32:47], v[206:209], v[96:99], v[32:47]
	ds_read_b128 v[206:209], v247 offset:23104
	v_exp_f32_e32 v106, v106
	v_exp_f32_e32 v107, v107
	v_add_f32_e32 v242, v242, v106
	v_add_f32_e32 v243, v243, v107
	s_waitcnt lgkmcnt(11)
	v_mfma_f32_32x32x16_bf16 v[16:31], v[210:213], v[96:99], v[16:31]
	ds_read_b128 v[210:213], v247 offset:27712
	v_exp_f32_e32 v108, v108
	v_exp_f32_e32 v109, v109
	v_add_f32_e32 v242, v242, v108
	v_add_f32_e32 v243, v243, v109
	s_waitcnt lgkmcnt(11)
	v_mfma_f32_32x32x16_bf16 v[0:15], v[214:217], v[96:99], v[0:15]
	ds_read_b128 v[214:217], v247 offset:32320
	v_exp_f32_e32 v110, v110
	v_exp_f32_e32 v111, v111
	v_add_f32_e32 v242, v242, v110
	v_add_f32_e32 v243, v243, v111
	v_cvt_pk_bf16_f32 v104, v104, v105
	v_cvt_pk_bf16_f32 v105, v106, v107
	v_cvt_pk_bf16_f32 v106, v108, v109
	v_cvt_pk_bf16_f32 v107, v110, v111
	s_nop 0
	s_waitcnt lgkmcnt(7)
	v_mfma_f32_32x32x16_bf16 v[48:63], v[218:221], v[104:107], v[48:63]
	ds_read_b128 v[218:221], v247 offset:18528
	v_exp_f32_e32 v80, v80
	v_exp_f32_e32 v81, v81
	v_exp_f32_e32 v82, v82
	s_waitcnt lgkmcnt(7)
	v_mfma_f32_32x32x16_bf16 v[32:47], v[222:225], v[104:107], v[32:47]
	ds_read_b128 v[222:225], v247 offset:23136
	v_exp_f32_e32 v83, v83
	v_add_f32_e32 v244, v80, v82
	v_add_f32_e32 v245, v81, v83
	v_exp_f32_e32 v84, v84
	s_waitcnt lgkmcnt(7)
	v_mfma_f32_32x32x16_bf16 v[16:31], v[226:229], v[104:107], v[16:31]
	ds_read_b128 v[226:229], v247 offset:27744
	v_exp_f32_e32 v85, v85
	v_add_f32_e32 v244, v244, v84
	v_add_f32_e32 v245, v245, v85
	v_exp_f32_e32 v86, v86
	s_waitcnt lgkmcnt(7)
	v_mfma_f32_32x32x16_bf16 v[0:15], v[152:155], v[104:107], v[0:15]
	ds_read_b128 v[152:155], v247 offset:32352
	v_exp_f32_e32 v87, v87
	v_add_f32_e32 v244, v244, v86
	v_add_f32_e32 v245, v245, v87
	v_cvt_pk_bf16_f32 v80, v80, v81
	v_cvt_pk_bf16_f32 v81, v82, v83
	v_cvt_pk_bf16_f32 v82, v84, v85
	v_cvt_pk_bf16_f32 v83, v86, v87
	s_nop 0
	s_waitcnt lgkmcnt(7)
	v_mfma_f32_32x32x16_bf16 v[48:63], v[202:205], v[80:83], v[48:63]
	v_exp_f32_e32 v88, v88
	v_exp_f32_e32 v89, v89
	v_add_f32_e32 v244, v244, v88
	v_add_f32_e32 v245, v245, v89
	s_waitcnt lgkmcnt(6)
	v_mfma_f32_32x32x16_bf16 v[32:47], v[206:209], v[80:83], v[32:47]
	v_exp_f32_e32 v90, v90
	v_exp_f32_e32 v91, v91
	v_add_f32_e32 v244, v244, v90
	v_add_f32_e32 v245, v245, v91
	s_waitcnt lgkmcnt(5)
	v_mfma_f32_32x32x16_bf16 v[16:31], v[210:213], v[80:83], v[16:31]
	v_exp_f32_e32 v92, v92
	v_exp_f32_e32 v93, v93
	v_add_f32_e32 v244, v244, v92
	v_add_f32_e32 v245, v245, v93
	s_waitcnt lgkmcnt(4)
	v_mfma_f32_32x32x16_bf16 v[0:15], v[214:217], v[80:83], v[0:15]
	v_exp_f32_e32 v94, v94
	v_exp_f32_e32 v95, v95
	v_add_f32_e32 v244, v244, v94
	v_add_f32_e32 v245, v245, v95
	v_cvt_pk_bf16_f32 v88, v88, v89
	v_cvt_pk_bf16_f32 v89, v90, v91
	v_cvt_pk_bf16_f32 v90, v92, v93
	v_cvt_pk_bf16_f32 v91, v94, v95
	s_nop 0
	s_waitcnt lgkmcnt(3)
	v_mfma_f32_32x32x16_bf16 v[48:63], v[218:221], v[88:91], v[48:63]
	v_add_f32_e32 v242, v242, v243
	v_add_f32_e32 v244, v244, v245
	s_waitcnt lgkmcnt(2)
	v_mfma_f32_32x32x16_bf16 v[32:47], v[222:225], v[88:91], v[32:47]
	v_add_f32_e32 v242, v242, v244
	s_waitcnt lgkmcnt(1)
	v_mfma_f32_32x32x16_bf16 v[16:31], v[226:229], v[88:91], v[16:31]
	s_waitcnt lgkmcnt(0)
	v_mfma_f32_32x32x16_bf16 v[0:15], v[152:155], v[88:91], v[0:15]
	v_cmp_lt_f32_e32 vcc, s33, v242
	s_cbranch_vccz .Ldf_norescale
	s_nop 15
	ds_bpermute_b32 v156, v230, v242
	s_waitcnt lgkmcnt(0)
	v_add_f32_e32 v156, v156, v242
	v_frexp_exp_i32_f32_e32 v156, v156
	v_max_i32_e32 v156, 1, v156
	v_add_u32_e32 v156, -1, v156
	v_cvt_f32_u32_e32 v156, v156
	v_exp_f32_e64 v157, -v156
	v_add_f32_e32 v165, v165, v156
	v_xor_b32_e32 v64, 0x80000000, v165
	v_mul_f32_e32 v164, v164, v157
	v_mul_f32_e32 v242, v242, v157
	v_mul_f32_e32 v0, v0, v157
	v_mul_f32_e32 v1, v1, v157
	v_mul_f32_e32 v2, v2, v157
	v_mul_f32_e32 v3, v3, v157
	v_mul_f32_e32 v4, v4, v157
	v_mul_f32_e32 v5, v5, v157
	v_mul_f32_e32 v6, v6, v157
	v_mul_f32_e32 v7, v7, v157
	v_mul_f32_e32 v8, v8, v157
	v_mul_f32_e32 v9, v9, v157
	v_mul_f32_e32 v10, v10, v157
	v_mul_f32_e32 v11, v11, v157
	v_mul_f32_e32 v12, v12, v157
	v_mul_f32_e32 v13, v13, v157
	v_mul_f32_e32 v14, v14, v157
	v_mul_f32_e32 v15, v15, v157
	v_mul_f32_e32 v16, v16, v157
	v_mul_f32_e32 v17, v17, v157
	v_mul_f32_e32 v18, v18, v157
	v_mul_f32_e32 v19, v19, v157
	v_mul_f32_e32 v20, v20, v157
	v_mul_f32_e32 v21, v21, v157
	v_mul_f32_e32 v22, v22, v157
	v_mul_f32_e32 v23, v23, v157
	v_mul_f32_e32 v24, v24, v157
	v_mul_f32_e32 v25, v25, v157
	v_mul_f32_e32 v26, v26, v157
	v_mul_f32_e32 v27, v27, v157
	v_mul_f32_e32 v28, v28, v157
	v_mul_f32_e32 v29, v29, v157
	v_mul_f32_e32 v30, v30, v157
	v_mul_f32_e32 v31, v31, v157
	v_mul_f32_e32 v32, v32, v157
	v_mul_f32_e32 v33, v33, v157
	v_mul_f32_e32 v34, v34, v157
	v_mul_f32_e32 v35, v35, v157
	v_mul_f32_e32 v36, v36, v157
	v_mul_f32_e32 v37, v37, v157
	v_mul_f32_e32 v38, v38, v157
	v_mul_f32_e32 v39, v39, v157
	v_mul_f32_e32 v40, v40, v157
	v_mul_f32_e32 v41, v41, v157
	v_mul_f32_e32 v42, v42, v157
	v_mul_f32_e32 v43, v43, v157
	v_mul_f32_e32 v44, v44, v157
	v_mul_f32_e32 v45, v45, v157
	v_mul_f32_e32 v46, v46, v157
	v_mul_f32_e32 v47, v47, v157
	v_mul_f32_e32 v48, v48, v157
	v_mul_f32_e32 v49, v49, v157
	v_mul_f32_e32 v50, v50, v157
	v_mul_f32_e32 v51, v51, v157
	v_mul_f32_e32 v52, v52, v157
	v_mul_f32_e32 v53, v53, v157
	v_mul_f32_e32 v54, v54, v157
	v_mul_f32_e32 v55, v55, v157
	v_mul_f32_e32 v56, v56, v157
	v_mul_f32_e32 v57, v57, v157
	v_mul_f32_e32 v58, v58, v157
	v_mul_f32_e32 v59, v59, v157
	v_mul_f32_e32 v60, v60, v157
	v_mul_f32_e32 v61, v61, v157
	v_mul_f32_e32 v62, v62, v157
	v_mul_f32_e32 v63, v63, v157
	v_mov_b32_e32 v65, v64
	v_mov_b32_e32 v66, v64
	v_mov_b32_e32 v67, v64
	v_mov_b32_e32 v68, v64
	v_mov_b32_e32 v69, v64
	v_mov_b32_e32 v70, v64
	v_mov_b32_e32 v71, v64
	v_mov_b32_e32 v72, v64
	v_mov_b32_e32 v73, v64
	v_mov_b32_e32 v74, v64
	v_mov_b32_e32 v75, v64
	v_mov_b32_e32 v76, v64
	v_mov_b32_e32 v77, v64
	v_mov_b32_e32 v78, v64
	v_mov_b32_e32 v79, v64
.Ldf_norescale:
	v_add_f32_e32 v164, v164, v242
	s_add_i32 s14, s14, 1
	s_cmpk_lg_i32 s14, 0x80
	s_nop 3
	s_waitcnt lgkmcnt(0)
	s_barrier
	s_cbranch_scc1 .Ldf_body
	s_branch .LBB0_552
